# v34 + MLA loop: waves 4-7 run a copy with softmax VALU blocks moved across the tile barriers (VALU stagger, LDS/barriers unchanged)
# baseline (speedup 1.0000x reference)
.LBB0_542:
	v_cndmask_b32_e64 v202, v50, v1, s[2:3]
	v_mul_f32_e32 v50, 0xbdd53b94, v202
	v_fmamk_f32 v35, v35, 0x3dd53b94, v50
	v_fmamk_f32 v34, v34, 0x3dd53b94, v50
	v_fmamk_f32 v36, v36, 0x3dd53b94, v50
	v_exp_f32_e32 v231, v35
	v_lshlrev_b32_e32 v35, 4, v161
	v_exp_f32_e32 v229, v34
	v_exp_f32_e32 v227, v36
	v_lshlrev_b32_e32 v34, 3, v161
	v_and_b32_e32 v35, 0xc0, v35
	v_lshlrev_b32_e32 v36, 1, v161
	v_and_or_b32 v35, v34, 24, v35
	v_and_b32_e32 v36, 32, v36
	v_and_b32_e32 v34, 0x100, v34
	s_cmp_lg_u32 0, -1
	v_fmamk_f32 v37, v37, 0x3dd53b94, v50
	v_fmamk_f32 v38, v38, 0x3dd53b94, v50
	v_fmamk_f32 v39, v39, 0x3dd53b94, v50
	v_fmamk_f32 v40, v40, 0x3dd53b94, v50
	v_fmamk_f32 v41, v41, 0x3dd53b94, v50
	v_fmamk_f32 v42, v42, 0x3dd53b94, v50
	v_fmamk_f32 v43, v43, 0x3dd53b94, v50
	v_fmamk_f32 v44, v44, 0x3dd53b94, v50
	v_fmamk_f32 v45, v45, 0x3dd53b94, v50
	v_fmamk_f32 v46, v46, 0x3dd53b94, v50
	v_fmamk_f32 v47, v47, 0x3dd53b94, v50
	v_fmamk_f32 v48, v48, 0x3dd53b94, v50
	v_fmamk_f32 v49, v49, 0x3dd53b94, v50
	v_or3_b32 v34, v35, v36, v34
	s_cselect_b32 s1, 0, 0
	v_exp_f32_e32 v230, v37
	v_exp_f32_e32 v226, v38
	v_exp_f32_e32 v228, v39
	v_exp_f32_e32 v224, v40
	v_exp_f32_e32 v225, v41
	v_exp_f32_e32 v221, v42
	v_exp_f32_e32 v223, v43
	v_exp_f32_e32 v220, v44
	v_exp_f32_e32 v222, v45
	v_exp_f32_e32 v217, v46
	v_exp_f32_e32 v219, v47
	v_exp_f32_e32 v216, v48
	v_exp_f32_e32 v218, v49
	v_add_u32_e32 v200, s1, v34
	s_and_b32 s1, s84, 7
	s_lshl_b32 s1, s1, 9
	s_waitcnt vmcnt(0)
	v_pk_fma_f32 v[146:147], v[32:33], s[34:35], v[50:51] op_sel_hi:[1,0,0]
	v_pk_fma_f32 v[148:149], v[30:31], s[34:35], v[50:51] op_sel_hi:[1,0,0]
	v_pk_fma_f32 v[150:151], v[28:29], s[34:35], v[50:51] op_sel_hi:[1,0,0]
	v_pk_fma_f32 v[152:153], v[26:27], s[34:35], v[50:51] op_sel_hi:[1,0,0]
	v_pk_fma_f32 v[154:155], v[24:25], s[34:35], v[50:51] op_sel_hi:[1,0,0]
	v_pk_fma_f32 v[156:157], v[22:23], s[34:35], v[50:51] op_sel_hi:[1,0,0]
	v_pk_fma_f32 v[162:163], v[20:21], s[34:35], v[50:51] op_sel_hi:[1,0,0]
	v_pk_fma_f32 v[164:165], v[18:19], s[34:35], v[50:51] op_sel_hi:[1,0,0]
	v_lshl_add_u32 v170, v168, 2, v51
	v_lshl_add_u32 v158, v52, 2, v51
	s_add_u32 s20, s4, s1
	v_mov_b64_e32 v[64:65], v[16:17]
	v_mov_b64_e32 v[48:49], v[16:17]
	v_mov_b64_e32 v[32:33], v[16:17]
	s_mov_b32 s17, 1
	s_mov_b32 s0, 0
	v_cmp_gt_u32_e64 s[2:3], 32, v161
	s_mov_b32 s19, 2
	s_addc_u32 s21, s5, 0
	v_mov_b32_e32 v171, 0
	v_mov_b64_e32 v[62:63], v[14:15]
	v_mov_b64_e32 v[60:61], v[12:13]
	v_mov_b64_e32 v[58:59], v[10:11]
	v_mov_b64_e32 v[56:57], v[8:9]
	v_mov_b64_e32 v[54:55], v[6:7]
	v_mov_b64_e32 v[52:53], v[4:5]
	v_mov_b64_e32 v[50:51], v[2:3]
	v_mov_b64_e32 v[46:47], v[14:15]
	v_mov_b64_e32 v[44:45], v[12:13]
	v_mov_b64_e32 v[42:43], v[10:11]
	v_mov_b64_e32 v[40:41], v[8:9]
	v_mov_b64_e32 v[38:39], v[6:7]
	v_mov_b64_e32 v[36:37], v[4:5]
	v_mov_b64_e32 v[34:35], v[2:3]
	v_mov_b64_e32 v[30:31], v[14:15]
	v_mov_b64_e32 v[28:29], v[12:13]
	v_mov_b64_e32 v[26:27], v[10:11]
	v_mov_b64_e32 v[24:25], v[8:9]
	v_mov_b64_e32 v[22:23], v[6:7]
	v_mov_b64_e32 v[20:21], v[4:5]
	v_mov_b64_e32 v[18:19], v[2:3]
	s_mov_b32 s22, 2
	s_waitcnt vmcnt(0)
	s_barrier
	v_mov_b32_e32 v245, v172
	v_ashrrev_i32_e32 v250, 4, v245
	v_xor_b32_e32 v246, v250, v245
	v_lshlrev_b32_e32 v246, 3, v246
	v_lshrrev_b32_e32 v247, 1, v245
	v_and_b32_e32 v246, 0x78, v246
	v_and_b32_e32 v255, 8, v247
	v_lshrrev_b32_e32 v247, 1, v250
	v_bfe_u32 v254, v245, 2, 2
	v_and_b32_e32 v248, 4, v247
	v_lshl_or_b32 v246, v250, 11, v246
	v_and_or_b32 v250, v250, s75, v255
	v_lshlrev_b32_e32 v247, 3, v245
	v_or3_b32 v250, v250, v248, v254
	v_and_b32_e32 v251, 0x60, v245
	v_and_b32_e32 v249, 24, v247
	v_lshlrev_b32_e32 v250, 11, v250
	v_or3_b32 v250, v250, v251, v249
	v_ashrrev_i32_e32 v247, 31, v246
	v_ashrrev_i32_e32 v251, 31, v250
	v_lshlrev_b64 v[246:247], 1, v[246:247]
	v_lshlrev_b64 v[248:249], 1, v[250:251]
	v_lshrrev_b32_e32 v255, 4, v245
	v_lshrrev_b32_e32 v254, 3, v245
	v_xor_b32_e32 v255, v255, v245
	v_mul_lo_u32 v254, v254, s76
	v_lshlrev_b32_e32 v255, 3, v255
	v_and_or_b32 v254, v255, 56, v254
	v_ashrrev_i32_e32 v255, 31, v254
	v_lshlrev_b64 v[250:251], 1, v[254:255]
	v_readfirstlane_b32 s99, v184
	s_nop 3
	s_cmpk_lt_u32 s99, 0x100
	s_cbranch_scc1 .LBB0_543
	s_branch .Lmla_y_entry
.Lmla_y_top:
	v_cndmask_b32_e64 v202, v202, v165, s[4:5]
	v_mul_f32_e32 v146, 0xbdd53b94, v202
	v_fmamk_f32 v82, v82, 0x3dd53b94, v146
	v_fmamk_f32 v83, v83, 0x3dd53b94, v146
	v_fmamk_f32 v84, v84, 0x3dd53b94, v146
	v_fmamk_f32 v85, v85, 0x3dd53b94, v146
	v_fmamk_f32 v86, v86, 0x3dd53b94, v146
	v_fmamk_f32 v87, v87, 0x3dd53b94, v146
	v_fmamk_f32 v88, v88, 0x3dd53b94, v146
	v_fmamk_f32 v89, v89, 0x3dd53b94, v146
	v_fmamk_f32 v90, v90, 0x3dd53b94, v146
	v_fmamk_f32 v91, v91, 0x3dd53b94, v146
	v_fmamk_f32 v92, v92, 0x3dd53b94, v146
	v_fmamk_f32 v93, v93, 0x3dd53b94, v146
	v_fmamk_f32 v94, v94, 0x3dd53b94, v146
	v_fmamk_f32 v95, v95, 0x3dd53b94, v146
	v_fmamk_f32 v96, v96, 0x3dd53b94, v146
	v_fmamk_f32 v97, v97, 0x3dd53b94, v146
	v_exp_f32_e32 v229, v82
	v_exp_f32_e32 v231, v83
	v_exp_f32_e32 v227, v84
	v_exp_f32_e32 v230, v85
	v_exp_f32_e32 v226, v86
	v_exp_f32_e32 v228, v87
	v_exp_f32_e32 v224, v88
	v_exp_f32_e32 v225, v89
	v_exp_f32_e32 v221, v90
	v_exp_f32_e32 v223, v91
	v_exp_f32_e32 v220, v92
	v_exp_f32_e32 v222, v93
	v_exp_f32_e32 v217, v94
	v_exp_f32_e32 v219, v95
	v_exp_f32_e32 v216, v96
	v_exp_f32_e32 v218, v97
	v_add_f32_e32 v82, v162, v163
	v_fmac_f32_e32 v82, v201, v171
	v_add_f32_e32 v171, v232, v233
	v_fmac_f32_e32 v171, v82, v164
	v_fma_f32 v164, v66, s34, v146
	v_fma_f32 v165, v67, s34, v146
	v_fma_f32 v162, v68, s34, v146
	v_fma_f32 v163, v69, s34, v146
	v_fma_f32 v156, v70, s34, v146
	v_fma_f32 v157, v71, s34, v146
	v_fma_f32 v154, v72, s34, v146
	v_fma_f32 v155, v73, s34, v146
	v_fma_f32 v152, v74, s34, v146
	v_fma_f32 v153, v75, s34, v146
	v_fma_f32 v150, v76, s34, v146
	v_fma_f32 v151, v77, s34, v146
	v_fma_f32 v148, v78, s34, v146
	v_fma_f32 v149, v79, s34, v146
	v_fma_f32 v147, v81, s34, v146
	v_fma_f32 v146, v80, s34, v146
	v_mov_b32_e32 v201, v215

.Lmla_y_547:
	v_cndmask_b32_e64 v165, v165, v202, s[4:5]
	v_mul_f32_e32 v154, 0xbdd53b94, v165
	v_fmamk_f32 v202, v69, 0x3dd53b94, v154
	v_fmamk_f32 v215, v70, 0x3dd53b94, v154
	v_fmamk_f32 v232, v79, 0x3dd53b94, v154
	v_fmamk_f32 v233, v80, 0x3dd53b94, v154
	v_fmamk_f32 v155, v66, 0x3dd53b94, v154
	v_fmamk_f32 v156, v67, 0x3dd53b94, v154
	v_fmamk_f32 v157, v68, 0x3dd53b94, v154
	v_fmamk_f32 v216, v71, 0x3dd53b94, v154
	v_fmamk_f32 v217, v72, 0x3dd53b94, v154
	v_fmamk_f32 v218, v73, 0x3dd53b94, v154
	v_fmamk_f32 v219, v74, 0x3dd53b94, v154
	v_fmamk_f32 v220, v75, 0x3dd53b94, v154
	v_fmamk_f32 v221, v76, 0x3dd53b94, v154
	v_fmamk_f32 v222, v77, 0x3dd53b94, v154
	v_fmamk_f32 v223, v78, 0x3dd53b94, v154
	v_fmamk_f32 v82, v82, 0x3dd53b94, v154
	v_fmamk_f32 v83, v83, 0x3dd53b94, v154
	v_fmamk_f32 v84, v84, 0x3dd53b94, v154
	v_fmamk_f32 v85, v85, 0x3dd53b94, v154
	v_fmamk_f32 v86, v86, 0x3dd53b94, v154
	v_fmamk_f32 v87, v87, 0x3dd53b94, v154
	v_fmamk_f32 v88, v88, 0x3dd53b94, v154
	v_fmamk_f32 v89, v89, 0x3dd53b94, v154
	v_fmamk_f32 v90, v90, 0x3dd53b94, v154
	v_fmamk_f32 v91, v91, 0x3dd53b94, v154
	v_fmamk_f32 v92, v92, 0x3dd53b94, v154
	v_fmamk_f32 v93, v93, 0x3dd53b94, v154
	v_fmamk_f32 v94, v94, 0x3dd53b94, v154
	v_fmamk_f32 v95, v95, 0x3dd53b94, v154
	v_fmamk_f32 v96, v96, 0x3dd53b94, v154
	v_fmamk_f32 v97, v97, 0x3dd53b94, v154
	v_exp_f32_e32 v224, v82
	v_exp_f32_e32 v225, v83
	v_exp_f32_e32 v226, v84
	v_exp_f32_e32 v227, v85
	v_exp_f32_e32 v228, v86
	v_exp_f32_e32 v229, v87
	v_exp_f32_e32 v230, v88
	v_exp_f32_e32 v231, v89
	v_exp_f32_e32 v234, v90
	v_exp_f32_e32 v235, v91
	v_exp_f32_e32 v236, v92
	v_exp_f32_e32 v237, v93
	v_exp_f32_e32 v238, v94
	v_exp_f32_e32 v239, v95
	v_exp_f32_e32 v240, v96
	v_exp_f32_e32 v241, v97
	v_fmac_f32_e32 v154, 0x3dd53b94, v81
	v_exp_f32_e32 v155, v155
	v_exp_f32_e32 v156, v156
	s_waitcnt vmcnt(0)
	s_add_i32 s0, s19, 1
	s_cmp_ge_u32 s0, s86
	s_cselect_b32 s98, 1, 0
	s_waitcnt vmcnt(0)
	s_barrier
.Lmla_y_549:
	ds_read_b128 v[66:69], v174 offset:32768
	ds_read_b128 v[70:73], v174 offset:40960
	ds_read_b128 v[146:149], v176 offset:32768
	ds_read_b128 v[150:153], v176 offset:40960
	s_waitcnt lgkmcnt(0)
	v_mfma_f32_32x32x16_bf16 v[82:97], v[66:69], v[142:145], 0
	v_exp_f32_e32 v157, v157
	v_exp_f32_e32 v202, v202
	v_exp_f32_e32 v215, v215
	v_exp_f32_e32 v216, v216
	v_exp_f32_e32 v217, v217
	v_exp_f32_e32 v218, v218
	v_exp_f32_e32 v219, v219
	v_mfma_f32_32x32x16_bf16 v[66:81], v[70:73], v[142:145], 0
	v_exp_f32_e32 v220, v220
	v_exp_f32_e32 v221, v221
	v_exp_f32_e32 v222, v222
	v_exp_f32_e32 v223, v223
	v_exp_f32_e32 v242, v232
	v_exp_f32_e32 v243, v233
	v_exp_f32_e32 v244, v154
	v_mfma_f32_32x32x16_bf16 v[82:97], v[146:149], v[138:141], v[82:97]
	v_mfma_f32_32x32x16_bf16 v[66:81], v[150:153], v[138:141], v[66:81]
	ds_read_b128 v[146:149], v178 offset:32768
	ds_read_b128 v[150:153], v178 offset:40960
	s_cmp_lg_u32 s98, 0
	s_cbranch_scc1 .Lmla_y_nopf
	s_add_u32 s0, s38, s20
	s_addc_u32 s1, s39, s21
	s_add_u32 s100, s0, s42
	s_addc_u32 s101, s1, s43
	s_mov_b32 m0, s93
	v_lshl_add_u64 v[254:255], v[246:247], 0, s[100:101]
	global_load_lds_dwordx4 v[254:255], off
	s_add_u32 s100, s0, s46
	s_addc_u32 s101, s1, s47
	s_mov_b32 m0, s94
	v_lshl_add_u64 v[254:255], v[246:247], 0, s[100:101]
	global_load_lds_dwordx4 v[254:255], off
	s_add_u32 s100, s0, s44
	s_addc_u32 s101, s1, s45
	s_add_i32 s98, s89, s24
	s_mov_b32 m0, s98
	v_lshl_add_u64 v[254:255], v[248:249], 0, s[100:101]
	global_load_lds_dwordx4 v[254:255], off
	s_add_u32 s100, s0, s50
	s_addc_u32 s101, s1, s51
	s_add_i32 m0, s98, 0x2000
	v_lshl_add_u64 v[254:255], v[248:249], 0, s[100:101]
	global_load_lds_dwordx4 v[254:255], off
	s_add_u32 s0, s38, s88
	s_addc_u32 s1, s39, s87
	s_add_u32 s0, s0, s58
	s_addc_u32 s1, s1, s59
	s_mov_b32 m0, s95
	v_lshl_add_u64 v[254:255], v[250:251], 0, s[0:1]
	global_load_lds_dwordx4 v[254:255], off

.Lmla_y_553:
	s_add_u32 s88, s88, 0xf0000
	s_addc_u32 s87, s87, 0
	s_waitcnt vmcnt(0)
	s_add_u32 s20, s20, 0x80000
	s_addc_u32 s21, s21, 0
	s_add_i32 s19, s19, 2
	s_cmp_ge_u32 s19, s86
	s_mov_b32 s0, s22
	s_mov_b32 s22, s23
	s_waitcnt vmcnt(0)
	s_barrier
	s_cbranch_scc0 .Lmla_y_top
	v_cndmask_b32_e64 v202, v202, v165, s[4:5]
	v_mul_f32_e32 v146, 0xbdd53b94, v202
	v_fmamk_f32 v82, v82, 0x3dd53b94, v146
	v_fmamk_f32 v83, v83, 0x3dd53b94, v146
	v_fmamk_f32 v84, v84, 0x3dd53b94, v146
	v_fmamk_f32 v85, v85, 0x3dd53b94, v146
	v_fmamk_f32 v86, v86, 0x3dd53b94, v146
	v_fmamk_f32 v87, v87, 0x3dd53b94, v146
	v_fmamk_f32 v88, v88, 0x3dd53b94, v146
	v_fmamk_f32 v89, v89, 0x3dd53b94, v146
	v_fmamk_f32 v90, v90, 0x3dd53b94, v146
	v_fmamk_f32 v91, v91, 0x3dd53b94, v146
	v_fmamk_f32 v92, v92, 0x3dd53b94, v146
	v_fmamk_f32 v93, v93, 0x3dd53b94, v146
	v_fmamk_f32 v94, v94, 0x3dd53b94, v146
	v_fmamk_f32 v95, v95, 0x3dd53b94, v146
	v_fmamk_f32 v96, v96, 0x3dd53b94, v146
	v_fmamk_f32 v97, v97, 0x3dd53b94, v146
	v_exp_f32_e32 v229, v82
	v_exp_f32_e32 v231, v83
	v_exp_f32_e32 v227, v84
	v_exp_f32_e32 v230, v85
	v_exp_f32_e32 v226, v86
	v_exp_f32_e32 v228, v87
	v_exp_f32_e32 v224, v88
	v_exp_f32_e32 v225, v89
	v_exp_f32_e32 v221, v90
	v_exp_f32_e32 v223, v91
	v_exp_f32_e32 v220, v92
	v_exp_f32_e32 v222, v93
	v_exp_f32_e32 v217, v94
	v_exp_f32_e32 v219, v95
	v_exp_f32_e32 v216, v96
	v_exp_f32_e32 v218, v97
	v_add_f32_e32 v82, v162, v163
	v_fmac_f32_e32 v82, v201, v171
	v_add_f32_e32 v171, v232, v233
	v_fmac_f32_e32 v171, v82, v164
	v_fma_f32 v164, v66, s34, v146
	v_fma_f32 v165, v67, s34, v146
	v_fma_f32 v162, v68, s34, v146
	v_fma_f32 v163, v69, s34, v146
	v_fma_f32 v156, v70, s34, v146
	v_fma_f32 v157, v71, s34, v146
	v_fma_f32 v154, v72, s34, v146
	v_fma_f32 v155, v73, s34, v146
	v_fma_f32 v152, v74, s34, v146
	v_fma_f32 v153, v75, s34, v146
	v_fma_f32 v150, v76, s34, v146
	v_fma_f32 v151, v77, s34, v146
	v_fma_f32 v148, v78, s34, v146
	v_fma_f32 v149, v79, s34, v146
	v_fma_f32 v147, v81, s34, v146
	v_fma_f32 v146, v80, s34, v146
	v_mov_b32_e32 v201, v215
	s_branch .LBB0_555
